# IN_DA value-column epilogue hand-written: transposed bf16 tile staged through a wave-private LDS patch, 4 rows x 256 B per store
# baseline (speedup 1.0000x reference)
.LBB0_57:
	s_cmp_gt_i32 s70, 2
	s_cselect_b64 s[0:1], -1, 0
	s_cmp_lt_i32 s71, 3
	s_cselect_b64 s[2:3], -1, 0
	s_or_b64 s[0:1], s[0:1], s[2:3]
	s_and_b64 vcc, exec, s[0:1]
	s_mov_b64 s[0:1], s[80:81]
	s_mov_b64 s[12:13], s[92:93]
	v_writelane_b32 v241, s78, 36
	s_mov_b64 s[2:3], s[82:83]
	s_mov_b64 s[4:5], s[84:85]
	s_mov_b64 s[6:7], s[86:87]
	s_mov_b64 s[8:9], s[88:89]
	s_mov_b64 s[14:15], s[94:95]
	v_writelane_b32 v241, s0, 37
	s_nop 1
	v_writelane_b32 v241, s1, 38
	v_writelane_b32 v241, s2, 39
	v_writelane_b32 v241, s3, 40
	v_writelane_b32 v241, s4, 41
	v_writelane_b32 v241, s5, 42
	v_writelane_b32 v241, s6, 43
	v_writelane_b32 v241, s7, 44
	v_writelane_b32 v241, s8, 45
	v_writelane_b32 v241, s9, 46
	v_writelane_b32 v241, s10, 47
	v_writelane_b32 v241, s11, 48
	v_writelane_b32 v241, s12, 49
	v_writelane_b32 v241, s13, 50
	v_writelane_b32 v241, s14, 51
	v_writelane_b32 v241, s15, 52
	s_cbranch_vccnz .LBB0_682
	v_readlane_b32 s5, v241, 0
	s_and_b32 s0, s78, 7
	s_lshr_b32 s4, s5, 3
	s_cmp_eq_u32 s0, 0
	s_cselect_b64 s[0:1], -1, 0
	s_and_b64 s[2:3], s[0:1], exec
	s_movk_i32 s2, 0xc0
	s_cselect_b32 s55, s4, s5
	s_cselect_b32 s33, s2, 0x600
	s_cmp_ge_i32 s55, s33
	s_mov_b32 s15, 0
	s_cbranch_scc1 .LBB0_663
	v_readlane_b32 s16, v241, 37
	v_readlane_b32 s17, v241, 38
	v_readlane_b32 s18, v241, 39
	v_readlane_b32 s19, v241, 40
	v_readlane_b32 s28, v241, 49
	v_readlane_b32 s29, v241, 50
	s_add_u32 s80, s68, 0x13000000
	v_readlane_b32 s30, v241, 51
	v_readlane_b32 s31, v241, 52
	s_mov_b64 s[16:17], s[28:29]
	s_addc_u32 s81, s69, 0
	s_mov_b64 s[18:19], s[30:31]
	s_add_u32 s82, s18, 0x12000000
	s_addc_u32 s83, s19, 0
	s_add_u32 s84, s68, 0x12000000
	v_readlane_b32 s3, v241, 0
	v_readlane_b32 s6, v241, 36
	s_addc_u32 s17, s69, 0
	s_and_b32 s85, s3, 7
	s_ashr_i32 s3, s6, 3
	s_and_b64 s[4:5], s[0:1], exec
	s_cselect_b32 s86, s3, s6
	s_add_u32 s88, s68, 0x14080000
	s_addc_u32 s89, s69, 0
	s_add_u32 s92, s18, 0x6000000
	v_readlane_b32 s20, v241, 41
	s_addc_u32 s93, s19, 0
	v_readlane_b32 s21, v241, 42
	s_add_u32 s20, s68, 0x3000000
	v_readlane_b32 s22, v241, 43
	s_addc_u32 s21, s69, 0
	v_readlane_b32 s23, v241, 44
	v_lshrrev_b32_e32 v1, 4, v178
	v_bfe_u32 v0, v178, 4, 2
	v_and_b32_e32 v2, 7, v178
	s_add_u32 s22, s68, 0x4000000
	v_readlane_b32 s24, v241, 45
	v_bitop3_b32 v3, v1, v2, 3 bitop3:0x6c
	v_bitop3_b32 v2, v0, v2, 4 bitop3:0x36
	v_lshlrev_b32_e32 v0, 7, v178
	s_addc_u32 s23, s69, 0
	v_readlane_b32 s25, v241, 46
	v_and_b32_e32 v4, 0x1c00, v0
	s_add_u32 s24, s18, 0xa000000
	v_readlane_b32 s26, v241, 47
	v_lshl_or_b32 v0, v3, 3, v4
	v_bfe_u32 v3, v178, 1, 3
	s_addc_u32 s25, s19, 0
	v_readlane_b32 s27, v241, 48
	v_bitop3_b32 v1, v1, v3, 3 bitop3:0x6c
	s_add_u32 s26, s68, 0x6800000
	v_lshl_or_b32 v2, v2, 3, v4
	v_mov_b32_e32 v129, 0
	v_lshlrev_b32_e32 v155, 4, v1
	v_lshrrev_b32_e32 v1, 2, v178
	s_addc_u32 s27, s69, 0
	v_and_b32_e32 v158, 12, v1
	v_and_b32_e32 v161, 0x4f, v178
	s_add_u32 s28, s68, 0x7800000
	v_lshlrev_b32_e32 v130, 1, v0
	v_mov_b32_e32 v131, v129
	v_lshlrev_b32_e32 v134, 1, v2
	v_mov_b32_e32 v135, v129
	v_cndmask_b32_e64 v1, 0, 1, s[0:1]
	v_and_b32_e32 v154, 15, v178
	v_xor_b32_e32 v156, 64, v155
	v_lshlrev_b32_e32 v157, 7, v180
	v_and_or_b32 v159, v178, s2, v158
	v_and_b32_e32 v160, 0xcf, v178
	v_or_b32_e32 v162, 16, v161
	v_or_b32_e32 v163, 32, v161
	v_or_b32_e32 v164, 48, v161
	s_addc_u32 s29, s69, 0
	v_lshl_add_u64 v[132:133], s[68:69], 0, v[130:131]
	v_lshl_add_u64 v[136:137], s[68:69], 0, v[134:135]
	s_mov_b64 s[2:3], 0
	v_cmp_ne_u32_e64 s[94:95], 1, v1
	s_mov_b64 s[38:39], 0x80
	s_mov_b64 s[40:41], 0x12000080
	s_mov_b64 s[42:43], 0x4080
	s_mov_b64 s[44:45], 0x12004080
	s_mov_b64 s[46:47], 0x8080
	s_movk_i32 s34, 0x2000
	s_movk_i32 s35, 0x1fff
	s_movk_i32 s87, 0x7ff
	s_movk_i32 s36, 0x3ff
	s_movk_i32 s37, 0x1400
	v_lshlrev_b32_e32 v138, 1, v0
	v_lshlrev_b32_e32 v140, 1, v2
	v_mov_b32_e32 v165, 0x8f
	v_mov_b32_e32 v166, 0x78f
	v_mov_b32_e32 v167, 0x9f
	v_mov_b32_e32 v168, 0x79f
	v_mov_b32_e32 v169, 0xaf
	v_mov_b32_e32 v170, 0x7af
	v_mov_b32_e32 v171, 0xbf
	v_mov_b32_e32 v172, 0x7bf
	v_mov_b32_e32 v173, 0xcf
	v_mov_b32_e32 v174, 0x7cf
	v_mov_b32_e32 v175, 0xdf
	v_mov_b32_e32 v176, 0x7df
	v_mov_b32_e32 v177, 0xef
	v_mov_b32_e32 v187, 0x7ef
	v_mov_b32_e32 v188, 0xff
	v_mov_b32_e32 v189, 0x7ff
	v_mov_b32_e32 v190, 0x50
	v_mov_b32_e32 v191, 0x60
	v_mov_b32_e32 v192, 0x70
	s_mov_b64 s[48:49], 0x12008080
	s_mov_b64 s[50:51], 0xc080
	s_mov_b64 s[52:53], 0x1200c080
	s_mov_b32 s54, 0x3e38aa3b
	s_branch .LBB0_62
.LBB0_61:
	s_mov_b64 s[2:3], -1
	s_and_b64 vcc, exec, s[56:57]
	s_cbranch_vccnz .LBB0_663

.LBB0_535:
	v_readfirstlane_b32 s100, v178
	s_nop 0
	s_lshr_b32 s100, s100, 6
	s_lshr_b32 s101, s100, 2
	s_and_b32 s100, s100, 3
	s_lshl_b32 s101, s101, 7
	s_add_i32 s101, s101, s16
	s_lshl_b32 s100, s100, 6
	v_readfirstlane_b32 s4, v178
	s_nop 0
	s_lshr_b32 s4, s4, 6
	s_mul_i32 s4, s4, 4352
	s_add_i32 s4, s4, 0x10000
	v_and_b32_e32 v245, 15, v178
	v_bfe_u32 v246, v178, 4, 2
	v_mul_u32_u24_e32 v242, 272, v245
	v_mul_u32_u24_e32 v243, 272, v246
	v_lshl_add_u32 v242, v246, 3, v242
	v_lshl_add_u32 v243, v245, 4, v243
	v_add_u32_e32 v242, s4, v242
	v_add_u32_e32 v243, s4, v243
	s_sub_i32 s2, s58, 0x800
	s_add_i32 s2, s2, s100
	s_lshr_b32 s3, s2, 7
	s_and_b32 s4, s2, 0x7f
	s_cmpk_ge_u32 s16, 0x2000
	s_cbranch_scc1 .Lepiv102_smp
	s_lshr_b32 s5, s101, 8
	s_lshl_b32 s6, s5, 3
	s_add_i32 s6, s6, s3
	s_lshl_b32 s6, s6, 7
	s_add_i32 s6, s6, s4
	s_lshl_b32 s6, s6, 9
	s_and_b32 s7, s101, 0xff
	s_lshl_b32 vcc_lo, s7, 1
	s_add_u32 s6, s6, vcc_lo
	s_add_u32 s98, s26, s6
	s_addc_u32 s99, s27, 0
	s_lshl_b32 s5, s5, 1
	s_lshl_b32 s5, s5, 8
	s_add_i32 s5, s5, s7
	s_lshl_b32 s5, s5, 12
	s_lshl_b32 s2, s2, 2
	s_add_u32 s5, s5, s2
	s_add_u32 s2, s24, s5
	s_addc_u32 s3, s25, 0
	s_movk_i32 s7, 0x800
	v_lshlrev_b32_e32 v244, 9, v246
	v_lshl_add_u32 v244, v245, 4, v244
	v_lshlrev_b32_e32 v247, 14, v246
	v_lshl_add_u32 v247, v245, 2, v247
	v_add_u32_e32 v248, 0x1000, v247
	v_add_u32_e32 v249, 0x2000, v247
	v_add_u32_e32 v250, 0x3000, v247
	global_store_dword v247, v124, s[2:3]
	global_store_dword v248, v125, s[2:3]
	global_store_dword v249, v126, s[2:3]
	global_store_dword v250, v127, s[2:3]
	s_add_u32 s2, s2, 0x10000
	s_addc_u32 s3, s3, 0
	v_cvt_pk_bf16_f32 v124, v124, v125
	v_cvt_pk_bf16_f32 v125, v126, v127
	ds_write_b64 v242, v[124:125]
	global_store_dword v247, v108, s[2:3]
	global_store_dword v248, v109, s[2:3]
	global_store_dword v249, v110, s[2:3]
	global_store_dword v250, v111, s[2:3]
	s_add_u32 s2, s2, 0x10000
	s_addc_u32 s3, s3, 0
	v_cvt_pk_bf16_f32 v108, v108, v109
	v_cvt_pk_bf16_f32 v109, v110, v111
	ds_write_b64 v242, v[108:109] offset:32
	global_store_dword v247, v92, s[2:3]
	global_store_dword v248, v93, s[2:3]
	global_store_dword v249, v94, s[2:3]
	global_store_dword v250, v95, s[2:3]
	s_add_u32 s2, s2, 0x10000
	s_addc_u32 s3, s3, 0
	v_cvt_pk_bf16_f32 v92, v92, v93
	v_cvt_pk_bf16_f32 v93, v94, v95
	ds_write_b64 v242, v[92:93] offset:64
	global_store_dword v247, v76, s[2:3]
	global_store_dword v248, v77, s[2:3]
	global_store_dword v249, v78, s[2:3]
	global_store_dword v250, v79, s[2:3]
	s_add_u32 s2, s2, 0x10000
	s_addc_u32 s3, s3, 0
	v_cvt_pk_bf16_f32 v76, v76, v77
	v_cvt_pk_bf16_f32 v77, v78, v79
	ds_write_b64 v242, v[76:77] offset:96
	global_store_dword v247, v60, s[2:3]
	global_store_dword v248, v61, s[2:3]
	global_store_dword v249, v62, s[2:3]
	global_store_dword v250, v63, s[2:3]
	s_add_u32 s2, s2, 0x10000
	s_addc_u32 s3, s3, 0
	v_cvt_pk_bf16_f32 v60, v60, v61
	v_cvt_pk_bf16_f32 v61, v62, v63
	ds_write_b64 v242, v[60:61] offset:128
	global_store_dword v247, v44, s[2:3]
	global_store_dword v248, v45, s[2:3]
	global_store_dword v249, v46, s[2:3]
	global_store_dword v250, v47, s[2:3]
	s_add_u32 s2, s2, 0x10000
	s_addc_u32 s3, s3, 0
	v_cvt_pk_bf16_f32 v44, v44, v45
	v_cvt_pk_bf16_f32 v45, v46, v47
	ds_write_b64 v242, v[44:45] offset:160
	global_store_dword v247, v28, s[2:3]
	global_store_dword v248, v29, s[2:3]
	global_store_dword v249, v30, s[2:3]
	global_store_dword v250, v31, s[2:3]
	s_add_u32 s2, s2, 0x10000
	s_addc_u32 s3, s3, 0
	v_cvt_pk_bf16_f32 v28, v28, v29
	v_cvt_pk_bf16_f32 v29, v30, v31
	ds_write_b64 v242, v[28:29] offset:192
	global_store_dword v247, v12, s[2:3]
	global_store_dword v248, v13, s[2:3]
	global_store_dword v249, v14, s[2:3]
	global_store_dword v250, v15, s[2:3]
	s_sub_u32 s2, s2, 0x70000
	s_subb_u32 s3, s3, 0
	v_cvt_pk_bf16_f32 v12, v12, v13
	v_cvt_pk_bf16_f32 v13, v14, v15
	ds_write_b64 v242, v[12:13] offset:224
	s_waitcnt lgkmcnt(0)
	ds_read_b128 v[124:127], v243
	ds_read_b128 v[108:111], v243 offset:1088
	ds_read_b128 v[92:95], v243 offset:2176
	ds_read_b128 v[76:79], v243 offset:3264
	s_waitcnt lgkmcnt(3)
	global_store_dwordx4 v244, v[124:127], s[98:99]
	s_add_u32 s98, s98, s7
	s_addc_u32 s99, s99, 0
	s_waitcnt lgkmcnt(2)
	global_store_dwordx4 v244, v[108:111], s[98:99]
	s_add_u32 s98, s98, s7
	s_addc_u32 s99, s99, 0
	s_waitcnt lgkmcnt(1)
	global_store_dwordx4 v244, v[92:95], s[98:99]
	s_add_u32 s98, s98, s7
	s_addc_u32 s99, s99, 0
	s_waitcnt lgkmcnt(0)
	global_store_dwordx4 v244, v[76:79], s[98:99]
	s_add_u32 s98, s98, s7
	s_addc_u32 s99, s99, 0
	global_store_dword v247, v120, s[2:3] offset:64
	global_store_dword v248, v121, s[2:3] offset:64
	global_store_dword v249, v122, s[2:3] offset:64
	global_store_dword v250, v123, s[2:3] offset:64
	s_add_u32 s2, s2, 0x10000
	s_addc_u32 s3, s3, 0
	v_cvt_pk_bf16_f32 v120, v120, v121
	v_cvt_pk_bf16_f32 v121, v122, v123
	ds_write_b64 v242, v[120:121]
	global_store_dword v247, v104, s[2:3] offset:64
	global_store_dword v248, v105, s[2:3] offset:64
	global_store_dword v249, v106, s[2:3] offset:64
	global_store_dword v250, v107, s[2:3] offset:64
	s_add_u32 s2, s2, 0x10000
	s_addc_u32 s3, s3, 0
	v_cvt_pk_bf16_f32 v104, v104, v105
	v_cvt_pk_bf16_f32 v105, v106, v107
	ds_write_b64 v242, v[104:105] offset:32
	global_store_dword v247, v88, s[2:3] offset:64
	global_store_dword v248, v89, s[2:3] offset:64
	global_store_dword v249, v90, s[2:3] offset:64
	global_store_dword v250, v91, s[2:3] offset:64
	s_add_u32 s2, s2, 0x10000
	s_addc_u32 s3, s3, 0
	v_cvt_pk_bf16_f32 v88, v88, v89
	v_cvt_pk_bf16_f32 v89, v90, v91
	ds_write_b64 v242, v[88:89] offset:64
	global_store_dword v247, v72, s[2:3] offset:64
	global_store_dword v248, v73, s[2:3] offset:64
	global_store_dword v249, v74, s[2:3] offset:64
	global_store_dword v250, v75, s[2:3] offset:64
	s_add_u32 s2, s2, 0x10000
	s_addc_u32 s3, s3, 0
	v_cvt_pk_bf16_f32 v72, v72, v73
	v_cvt_pk_bf16_f32 v73, v74, v75
	ds_write_b64 v242, v[72:73] offset:96
	global_store_dword v247, v56, s[2:3] offset:64
	global_store_dword v248, v57, s[2:3] offset:64
	global_store_dword v249, v58, s[2:3] offset:64
	global_store_dword v250, v59, s[2:3] offset:64
	s_add_u32 s2, s2, 0x10000
	s_addc_u32 s3, s3, 0
	v_cvt_pk_bf16_f32 v56, v56, v57
	v_cvt_pk_bf16_f32 v57, v58, v59
	ds_write_b64 v242, v[56:57] offset:128
	global_store_dword v247, v40, s[2:3] offset:64
	global_store_dword v248, v41, s[2:3] offset:64
	global_store_dword v249, v42, s[2:3] offset:64
	global_store_dword v250, v43, s[2:3] offset:64
	s_add_u32 s2, s2, 0x10000
	s_addc_u32 s3, s3, 0
	v_cvt_pk_bf16_f32 v40, v40, v41
	v_cvt_pk_bf16_f32 v41, v42, v43
	ds_write_b64 v242, v[40:41] offset:160
	global_store_dword v247, v24, s[2:3] offset:64
	global_store_dword v248, v25, s[2:3] offset:64
	global_store_dword v249, v26, s[2:3] offset:64
	global_store_dword v250, v27, s[2:3] offset:64
	s_add_u32 s2, s2, 0x10000
	s_addc_u32 s3, s3, 0
	v_cvt_pk_bf16_f32 v24, v24, v25
	v_cvt_pk_bf16_f32 v25, v26, v27
	ds_write_b64 v242, v[24:25] offset:192
	global_store_dword v247, v8, s[2:3] offset:64
	global_store_dword v248, v9, s[2:3] offset:64
	global_store_dword v249, v10, s[2:3] offset:64
	global_store_dword v250, v11, s[2:3] offset:64
	s_sub_u32 s2, s2, 0x70000
	s_subb_u32 s3, s3, 0
	v_cvt_pk_bf16_f32 v8, v8, v9
	v_cvt_pk_bf16_f32 v9, v10, v11
	ds_write_b64 v242, v[8:9] offset:224
	s_waitcnt lgkmcnt(0)
	ds_read_b128 v[120:123], v243
	ds_read_b128 v[104:107], v243 offset:1088
	ds_read_b128 v[88:91], v243 offset:2176
	ds_read_b128 v[72:75], v243 offset:3264
	s_waitcnt lgkmcnt(3)
	global_store_dwordx4 v244, v[120:123], s[98:99]
	s_add_u32 s98, s98, s7
	s_addc_u32 s99, s99, 0
	s_waitcnt lgkmcnt(2)
	global_store_dwordx4 v244, v[104:107], s[98:99]
	s_add_u32 s98, s98, s7
	s_addc_u32 s99, s99, 0
	s_waitcnt lgkmcnt(1)
	global_store_dwordx4 v244, v[88:91], s[98:99]
	s_add_u32 s98, s98, s7
	s_addc_u32 s99, s99, 0
	s_waitcnt lgkmcnt(0)
	global_store_dwordx4 v244, v[72:75], s[98:99]
	s_add_u32 s98, s98, s7
	s_addc_u32 s99, s99, 0
	global_store_dword v247, v116, s[2:3] offset:128
	global_store_dword v248, v117, s[2:3] offset:128
	global_store_dword v249, v118, s[2:3] offset:128
	global_store_dword v250, v119, s[2:3] offset:128
	s_add_u32 s2, s2, 0x10000
	s_addc_u32 s3, s3, 0
	v_cvt_pk_bf16_f32 v116, v116, v117
	v_cvt_pk_bf16_f32 v117, v118, v119
	ds_write_b64 v242, v[116:117]
	global_store_dword v247, v100, s[2:3] offset:128
	global_store_dword v248, v101, s[2:3] offset:128
	global_store_dword v249, v102, s[2:3] offset:128
	global_store_dword v250, v103, s[2:3] offset:128
	s_add_u32 s2, s2, 0x10000
	s_addc_u32 s3, s3, 0
	v_cvt_pk_bf16_f32 v100, v100, v101
	v_cvt_pk_bf16_f32 v101, v102, v103
	ds_write_b64 v242, v[100:101] offset:32
	global_store_dword v247, v84, s[2:3] offset:128
	global_store_dword v248, v85, s[2:3] offset:128
	global_store_dword v249, v86, s[2:3] offset:128
	global_store_dword v250, v87, s[2:3] offset:128
	s_add_u32 s2, s2, 0x10000
	s_addc_u32 s3, s3, 0
	v_cvt_pk_bf16_f32 v84, v84, v85
	v_cvt_pk_bf16_f32 v85, v86, v87
	ds_write_b64 v242, v[84:85] offset:64
	global_store_dword v247, v68, s[2:3] offset:128
	global_store_dword v248, v69, s[2:3] offset:128
	global_store_dword v249, v70, s[2:3] offset:128
	global_store_dword v250, v71, s[2:3] offset:128
	s_add_u32 s2, s2, 0x10000
	s_addc_u32 s3, s3, 0
	v_cvt_pk_bf16_f32 v68, v68, v69
	v_cvt_pk_bf16_f32 v69, v70, v71
	ds_write_b64 v242, v[68:69] offset:96
	global_store_dword v247, v52, s[2:3] offset:128
	global_store_dword v248, v53, s[2:3] offset:128
	global_store_dword v249, v54, s[2:3] offset:128
	global_store_dword v250, v55, s[2:3] offset:128
	s_add_u32 s2, s2, 0x10000
	s_addc_u32 s3, s3, 0
	v_cvt_pk_bf16_f32 v52, v52, v53
	v_cvt_pk_bf16_f32 v53, v54, v55
	ds_write_b64 v242, v[52:53] offset:128
	global_store_dword v247, v36, s[2:3] offset:128
	global_store_dword v248, v37, s[2:3] offset:128
	global_store_dword v249, v38, s[2:3] offset:128
	global_store_dword v250, v39, s[2:3] offset:128
	s_add_u32 s2, s2, 0x10000
	s_addc_u32 s3, s3, 0
	v_cvt_pk_bf16_f32 v36, v36, v37
	v_cvt_pk_bf16_f32 v37, v38, v39
	ds_write_b64 v242, v[36:37] offset:160
	global_store_dword v247, v20, s[2:3] offset:128
	global_store_dword v248, v21, s[2:3] offset:128
	global_store_dword v249, v22, s[2:3] offset:128
	global_store_dword v250, v23, s[2:3] offset:128
	s_add_u32 s2, s2, 0x10000
	s_addc_u32 s3, s3, 0
	v_cvt_pk_bf16_f32 v20, v20, v21
	v_cvt_pk_bf16_f32 v21, v22, v23
	ds_write_b64 v242, v[20:21] offset:192
	global_store_dword v247, v4, s[2:3] offset:128
	global_store_dword v248, v5, s[2:3] offset:128
	global_store_dword v249, v6, s[2:3] offset:128
	global_store_dword v250, v7, s[2:3] offset:128
	s_sub_u32 s2, s2, 0x70000
	s_subb_u32 s3, s3, 0
	v_cvt_pk_bf16_f32 v4, v4, v5
	v_cvt_pk_bf16_f32 v5, v6, v7
	ds_write_b64 v242, v[4:5] offset:224
	s_waitcnt lgkmcnt(0)
	ds_read_b128 v[116:119], v243
	ds_read_b128 v[100:103], v243 offset:1088
	ds_read_b128 v[84:87], v243 offset:2176
	ds_read_b128 v[68:71], v243 offset:3264
	s_waitcnt lgkmcnt(3)
	global_store_dwordx4 v244, v[116:119], s[98:99]
	s_add_u32 s98, s98, s7
	s_addc_u32 s99, s99, 0
	s_waitcnt lgkmcnt(2)
	global_store_dwordx4 v244, v[100:103], s[98:99]
	s_add_u32 s98, s98, s7
	s_addc_u32 s99, s99, 0
	s_waitcnt lgkmcnt(1)
	global_store_dwordx4 v244, v[84:87], s[98:99]
	s_add_u32 s98, s98, s7
	s_addc_u32 s99, s99, 0
	s_waitcnt lgkmcnt(0)
	global_store_dwordx4 v244, v[68:71], s[98:99]
	s_add_u32 s98, s98, s7
	s_addc_u32 s99, s99, 0
	global_store_dword v247, v112, s[2:3] offset:192
	global_store_dword v248, v113, s[2:3] offset:192
	global_store_dword v249, v114, s[2:3] offset:192
	global_store_dword v250, v115, s[2:3] offset:192
	s_add_u32 s2, s2, 0x10000
	s_addc_u32 s3, s3, 0
	v_cvt_pk_bf16_f32 v112, v112, v113
	v_cvt_pk_bf16_f32 v113, v114, v115
	ds_write_b64 v242, v[112:113]
	global_store_dword v247, v96, s[2:3] offset:192
	global_store_dword v248, v97, s[2:3] offset:192
	global_store_dword v249, v98, s[2:3] offset:192
	global_store_dword v250, v99, s[2:3] offset:192
	s_add_u32 s2, s2, 0x10000
	s_addc_u32 s3, s3, 0
	v_cvt_pk_bf16_f32 v96, v96, v97
	v_cvt_pk_bf16_f32 v97, v98, v99
	ds_write_b64 v242, v[96:97] offset:32
	global_store_dword v247, v80, s[2:3] offset:192
	global_store_dword v248, v81, s[2:3] offset:192
	global_store_dword v249, v82, s[2:3] offset:192
	global_store_dword v250, v83, s[2:3] offset:192
	s_add_u32 s2, s2, 0x10000
	s_addc_u32 s3, s3, 0
	v_cvt_pk_bf16_f32 v80, v80, v81
	v_cvt_pk_bf16_f32 v81, v82, v83
	ds_write_b64 v242, v[80:81] offset:64
	global_store_dword v247, v64, s[2:3] offset:192
	global_store_dword v248, v65, s[2:3] offset:192
	global_store_dword v249, v66, s[2:3] offset:192
	global_store_dword v250, v67, s[2:3] offset:192
	s_add_u32 s2, s2, 0x10000
	s_addc_u32 s3, s3, 0
	v_cvt_pk_bf16_f32 v64, v64, v65
	v_cvt_pk_bf16_f32 v65, v66, v67
	ds_write_b64 v242, v[64:65] offset:96
	global_store_dword v247, v48, s[2:3] offset:192
	global_store_dword v248, v49, s[2:3] offset:192
	global_store_dword v249, v50, s[2:3] offset:192
	global_store_dword v250, v51, s[2:3] offset:192
	s_add_u32 s2, s2, 0x10000
	s_addc_u32 s3, s3, 0
	v_cvt_pk_bf16_f32 v48, v48, v49
	v_cvt_pk_bf16_f32 v49, v50, v51
	ds_write_b64 v242, v[48:49] offset:128
	global_store_dword v247, v32, s[2:3] offset:192
	global_store_dword v248, v33, s[2:3] offset:192
	global_store_dword v249, v34, s[2:3] offset:192
	global_store_dword v250, v35, s[2:3] offset:192
	s_add_u32 s2, s2, 0x10000
	s_addc_u32 s3, s3, 0
	v_cvt_pk_bf16_f32 v32, v32, v33
	v_cvt_pk_bf16_f32 v33, v34, v35
	ds_write_b64 v242, v[32:33] offset:160
	global_store_dword v247, v16, s[2:3] offset:192
	global_store_dword v248, v17, s[2:3] offset:192
	global_store_dword v249, v18, s[2:3] offset:192
	global_store_dword v250, v19, s[2:3] offset:192
	s_add_u32 s2, s2, 0x10000
	s_addc_u32 s3, s3, 0
	v_cvt_pk_bf16_f32 v16, v16, v17
	v_cvt_pk_bf16_f32 v17, v18, v19
	ds_write_b64 v242, v[16:17] offset:192
	global_store_dword v247, v0, s[2:3] offset:192
	global_store_dword v248, v1, s[2:3] offset:192
	global_store_dword v249, v2, s[2:3] offset:192
	global_store_dword v250, v3, s[2:3] offset:192
	s_sub_u32 s2, s2, 0x70000
	s_subb_u32 s3, s3, 0
	v_cvt_pk_bf16_f32 v0, v0, v1
	v_cvt_pk_bf16_f32 v1, v2, v3
	ds_write_b64 v242, v[0:1] offset:224
	s_waitcnt lgkmcnt(0)
	ds_read_b128 v[112:115], v243
	ds_read_b128 v[96:99], v243 offset:1088
	ds_read_b128 v[80:83], v243 offset:2176
	ds_read_b128 v[64:67], v243 offset:3264
	s_waitcnt lgkmcnt(3)
	global_store_dwordx4 v244, v[112:115], s[98:99]
	s_add_u32 s98, s98, s7
	s_addc_u32 s99, s99, 0
	s_waitcnt lgkmcnt(2)
	global_store_dwordx4 v244, v[96:99], s[98:99]
	s_add_u32 s98, s98, s7
	s_addc_u32 s99, s99, 0
	s_waitcnt lgkmcnt(1)
	global_store_dwordx4 v244, v[80:83], s[98:99]
	s_add_u32 s98, s98, s7
	s_addc_u32 s99, s99, 0
	s_waitcnt lgkmcnt(0)
	global_store_dwordx4 v244, v[64:67], s[98:99]
	s_branch .LBB0_61
.Lepiv102_smp:
	s_sub_i32 s5, s101, 0x2000
	s_lshr_b32 s6, s5, 11
	s_and_b32 s5, s5, 0x7ff
	s_lshl_b32 s6, s6, 3
	s_add_i32 s6, s6, s3
	s_lshl_b32 s6, s6, 7
	s_add_i32 s6, s6, s4
	s_mul_i32 s6, s6, 0x1400
	s_lshl_b32 s5, s5, 1
	s_add_u32 s6, s6, s5
	s_add_u32 s98, s28, s6
	s_addc_u32 s99, s29, 0
	s_movk_i32 s7, 0x5000
	v_mul_u32_u24_e32 v244, 0x1400, v246
	v_lshl_add_u32 v244, v245, 4, v244
	v_cvt_pk_bf16_f32 v124, v124, v125
	v_cvt_pk_bf16_f32 v125, v126, v127
	ds_write_b64 v242, v[124:125]
	v_cvt_pk_bf16_f32 v108, v108, v109
	v_cvt_pk_bf16_f32 v109, v110, v111
	ds_write_b64 v242, v[108:109] offset:32
	v_cvt_pk_bf16_f32 v92, v92, v93
	v_cvt_pk_bf16_f32 v93, v94, v95
	ds_write_b64 v242, v[92:93] offset:64
	v_cvt_pk_bf16_f32 v76, v76, v77
	v_cvt_pk_bf16_f32 v77, v78, v79
	ds_write_b64 v242, v[76:77] offset:96
	v_cvt_pk_bf16_f32 v60, v60, v61
	v_cvt_pk_bf16_f32 v61, v62, v63
	ds_write_b64 v242, v[60:61] offset:128
	v_cvt_pk_bf16_f32 v44, v44, v45
	v_cvt_pk_bf16_f32 v45, v46, v47
	ds_write_b64 v242, v[44:45] offset:160
	v_cvt_pk_bf16_f32 v28, v28, v29
	v_cvt_pk_bf16_f32 v29, v30, v31
	ds_write_b64 v242, v[28:29] offset:192
	v_cvt_pk_bf16_f32 v12, v12, v13
	v_cvt_pk_bf16_f32 v13, v14, v15
	ds_write_b64 v242, v[12:13] offset:224
	s_waitcnt lgkmcnt(0)
	ds_read_b128 v[124:127], v243
	ds_read_b128 v[108:111], v243 offset:1088
	ds_read_b128 v[92:95], v243 offset:2176
	ds_read_b128 v[76:79], v243 offset:3264
	s_waitcnt lgkmcnt(3)
	global_store_dwordx4 v244, v[124:127], s[98:99]
	s_add_u32 s98, s98, s7
	s_addc_u32 s99, s99, 0
	s_waitcnt lgkmcnt(2)
	global_store_dwordx4 v244, v[108:111], s[98:99]
	s_add_u32 s98, s98, s7
	s_addc_u32 s99, s99, 0
	s_waitcnt lgkmcnt(1)
	global_store_dwordx4 v244, v[92:95], s[98:99]
	s_add_u32 s98, s98, s7
	s_addc_u32 s99, s99, 0
	s_waitcnt lgkmcnt(0)
	global_store_dwordx4 v244, v[76:79], s[98:99]
	s_add_u32 s98, s98, s7
	s_addc_u32 s99, s99, 0
	v_cvt_pk_bf16_f32 v120, v120, v121
	v_cvt_pk_bf16_f32 v121, v122, v123
	ds_write_b64 v242, v[120:121]
	v_cvt_pk_bf16_f32 v104, v104, v105
	v_cvt_pk_bf16_f32 v105, v106, v107
	ds_write_b64 v242, v[104:105] offset:32
	v_cvt_pk_bf16_f32 v88, v88, v89
	v_cvt_pk_bf16_f32 v89, v90, v91
	ds_write_b64 v242, v[88:89] offset:64
	v_cvt_pk_bf16_f32 v72, v72, v73
	v_cvt_pk_bf16_f32 v73, v74, v75
	ds_write_b64 v242, v[72:73] offset:96
	v_cvt_pk_bf16_f32 v56, v56, v57
	v_cvt_pk_bf16_f32 v57, v58, v59
	ds_write_b64 v242, v[56:57] offset:128
	v_cvt_pk_bf16_f32 v40, v40, v41
	v_cvt_pk_bf16_f32 v41, v42, v43
	ds_write_b64 v242, v[40:41] offset:160
	v_cvt_pk_bf16_f32 v24, v24, v25
	v_cvt_pk_bf16_f32 v25, v26, v27
	ds_write_b64 v242, v[24:25] offset:192
	v_cvt_pk_bf16_f32 v8, v8, v9
	v_cvt_pk_bf16_f32 v9, v10, v11
	ds_write_b64 v242, v[8:9] offset:224
	s_waitcnt lgkmcnt(0)
	ds_read_b128 v[120:123], v243
	ds_read_b128 v[104:107], v243 offset:1088
	ds_read_b128 v[88:91], v243 offset:2176
	ds_read_b128 v[72:75], v243 offset:3264
	s_waitcnt lgkmcnt(3)
	global_store_dwordx4 v244, v[120:123], s[98:99]
	s_add_u32 s98, s98, s7
	s_addc_u32 s99, s99, 0
	s_waitcnt lgkmcnt(2)
	global_store_dwordx4 v244, v[104:107], s[98:99]
	s_add_u32 s98, s98, s7
	s_addc_u32 s99, s99, 0
	s_waitcnt lgkmcnt(1)
	global_store_dwordx4 v244, v[88:91], s[98:99]
	s_add_u32 s98, s98, s7
	s_addc_u32 s99, s99, 0
	s_waitcnt lgkmcnt(0)
	global_store_dwordx4 v244, v[72:75], s[98:99]
	s_add_u32 s98, s98, s7
	s_addc_u32 s99, s99, 0
	v_cvt_pk_bf16_f32 v116, v116, v117
	v_cvt_pk_bf16_f32 v117, v118, v119
	ds_write_b64 v242, v[116:117]
	v_cvt_pk_bf16_f32 v100, v100, v101
	v_cvt_pk_bf16_f32 v101, v102, v103
	ds_write_b64 v242, v[100:101] offset:32
	v_cvt_pk_bf16_f32 v84, v84, v85
	v_cvt_pk_bf16_f32 v85, v86, v87
	ds_write_b64 v242, v[84:85] offset:64
	v_cvt_pk_bf16_f32 v68, v68, v69
	v_cvt_pk_bf16_f32 v69, v70, v71
	ds_write_b64 v242, v[68:69] offset:96
	v_cvt_pk_bf16_f32 v52, v52, v53
	v_cvt_pk_bf16_f32 v53, v54, v55
	ds_write_b64 v242, v[52:53] offset:128
	v_cvt_pk_bf16_f32 v36, v36, v37
	v_cvt_pk_bf16_f32 v37, v38, v39
	ds_write_b64 v242, v[36:37] offset:160
	v_cvt_pk_bf16_f32 v20, v20, v21
	v_cvt_pk_bf16_f32 v21, v22, v23
	ds_write_b64 v242, v[20:21] offset:192
	v_cvt_pk_bf16_f32 v4, v4, v5
	v_cvt_pk_bf16_f32 v5, v6, v7
	ds_write_b64 v242, v[4:5] offset:224
	s_waitcnt lgkmcnt(0)
	ds_read_b128 v[116:119], v243
	ds_read_b128 v[100:103], v243 offset:1088
	ds_read_b128 v[84:87], v243 offset:2176
	ds_read_b128 v[68:71], v243 offset:3264
	s_waitcnt lgkmcnt(3)
	global_store_dwordx4 v244, v[116:119], s[98:99]
	s_add_u32 s98, s98, s7
	s_addc_u32 s99, s99, 0
	s_waitcnt lgkmcnt(2)
	global_store_dwordx4 v244, v[100:103], s[98:99]
	s_add_u32 s98, s98, s7
	s_addc_u32 s99, s99, 0
	s_waitcnt lgkmcnt(1)
	global_store_dwordx4 v244, v[84:87], s[98:99]
	s_add_u32 s98, s98, s7
	s_addc_u32 s99, s99, 0
	s_waitcnt lgkmcnt(0)
	global_store_dwordx4 v244, v[68:71], s[98:99]
	s_add_u32 s98, s98, s7
	s_addc_u32 s99, s99, 0
	v_cvt_pk_bf16_f32 v112, v112, v113
	v_cvt_pk_bf16_f32 v113, v114, v115
	ds_write_b64 v242, v[112:113]
	v_cvt_pk_bf16_f32 v96, v96, v97
	v_cvt_pk_bf16_f32 v97, v98, v99
	ds_write_b64 v242, v[96:97] offset:32
	v_cvt_pk_bf16_f32 v80, v80, v81
	v_cvt_pk_bf16_f32 v81, v82, v83
	ds_write_b64 v242, v[80:81] offset:64
	v_cvt_pk_bf16_f32 v64, v64, v65
	v_cvt_pk_bf16_f32 v65, v66, v67
	ds_write_b64 v242, v[64:65] offset:96
	v_cvt_pk_bf16_f32 v48, v48, v49
	v_cvt_pk_bf16_f32 v49, v50, v51
	ds_write_b64 v242, v[48:49] offset:128
	v_cvt_pk_bf16_f32 v32, v32, v33
	v_cvt_pk_bf16_f32 v33, v34, v35
	ds_write_b64 v242, v[32:33] offset:160
	v_cvt_pk_bf16_f32 v16, v16, v17
	v_cvt_pk_bf16_f32 v17, v18, v19
	ds_write_b64 v242, v[16:17] offset:192
	v_cvt_pk_bf16_f32 v0, v0, v1
	v_cvt_pk_bf16_f32 v1, v2, v3
	ds_write_b64 v242, v[0:1] offset:224
	s_waitcnt lgkmcnt(0)
	ds_read_b128 v[112:115], v243
	ds_read_b128 v[96:99], v243 offset:1088
	ds_read_b128 v[80:83], v243 offset:2176
	ds_read_b128 v[64:67], v243 offset:3264
	s_waitcnt lgkmcnt(3)
	global_store_dwordx4 v244, v[112:115], s[98:99]
	s_add_u32 s98, s98, s7
	s_addc_u32 s99, s99, 0
	s_waitcnt lgkmcnt(2)
	global_store_dwordx4 v244, v[96:99], s[98:99]
	s_add_u32 s98, s98, s7
	s_addc_u32 s99, s99, 0
	s_waitcnt lgkmcnt(1)
	global_store_dwordx4 v244, v[80:83], s[98:99]
	s_add_u32 s98, s98, s7
	s_addc_u32 s99, s99, 0
	s_waitcnt lgkmcnt(0)
	global_store_dwordx4 v244, v[64:67], s[98:99]
	s_branch .LBB0_61

.LBB0_1596:
	s_cmp_gt_i32 s70, 19
	s_cselect_b64 s[0:1], -1, 0
	s_cmp_lt_i32 s71, 20
	s_cselect_b64 s[2:3], -1, 0
	s_or_b64 s[0:1], s[0:1], s[2:3]
	s_and_b64 vcc, exec, s[0:1]
	s_cbranch_vccnz .LBB0_2221
	v_readlane_b32 s3, v241, 0
	s_and_b32 s0, s78, 7
	s_lshr_b32 s2, s3, 3
	s_cmp_eq_u32 s0, 0
	s_cselect_b64 s[12:13], -1, 0
	s_and_b64 s[0:1], s[12:13], exec
	s_movk_i32 s0, 0xc0
	s_cselect_b32 s33, s2, s3
	s_cselect_b32 s55, s0, 0x600
	s_cmp_ge_i32 s33, s55
	s_mov_b32 s15, 0
	s_cbranch_scc1 .LBB0_2202
	s_add_u32 s88, s68, 0x13000000
	s_addc_u32 s89, s69, 0
	s_add_u32 s90, s68, 0xf000000
	s_addc_u32 s91, s69, 0
	s_add_u32 s92, s68, 0x12000000
	v_readlane_b32 s1, v241, 0
	v_readlane_b32 s4, v241, 36
	s_addc_u32 s93, s69, 0
	s_and_b32 s94, s1, 7
	s_ashr_i32 s1, s4, 3
	s_and_b64 s[2:3], s[12:13], exec
	v_readlane_b32 s36, v241, 37
	s_cselect_b32 s97, s1, s4
	s_add_u32 s16, s68, 0x14080000
	v_readlane_b32 s50, v241, 51
	v_readlane_b32 s51, v241, 52
	s_addc_u32 s17, s69, 0
	s_mov_b64 s[26:27], s[50:51]
	s_add_u32 s18, s26, 0x6000000
	s_addc_u32 s19, s27, 0
	s_add_u32 s20, s68, 0x3000000
	s_addc_u32 s21, s69, 0
	v_lshrrev_b32_e32 v1, 4, v178
	v_bfe_u32 v0, v178, 4, 2
	s_waitcnt lgkmcnt(0)
	v_and_b32_e32 v2, 7, v178
	s_add_u32 s22, s68, 0x4000000
	v_bitop3_b32 v3, v1, v2, 3 bitop3:0x6c
	v_bitop3_b32 v2, v0, v2, 4 bitop3:0x36
	v_lshlrev_b32_e32 v0, 7, v178
	s_addc_u32 s23, s69, 0
	v_and_b32_e32 v4, 0x1c00, v0
	s_add_u32 s24, s26, 0xa000000
	v_lshl_or_b32 v0, v3, 3, v4
	v_bfe_u32 v3, v178, 1, 3
	s_addc_u32 s25, s27, 0
	v_bitop3_b32 v1, v1, v3, 3 bitop3:0x6c
	s_add_u32 s26, s68, 0x6800000
	v_lshl_or_b32 v2, v2, 3, v4
	s_waitcnt vmcnt(0)
	v_mov_b32_e32 v129, 0
	v_lshlrev_b32_e32 v155, 4, v1
	v_lshrrev_b32_e32 v1, 2, v178
	s_addc_u32 s27, s69, 0
	v_and_b32_e32 v158, 12, v1
	v_and_b32_e32 v161, 0x4f, v178
	v_readlane_b32 s38, v241, 39
	v_readlane_b32 s39, v241, 40
	v_readlane_b32 s40, v241, 41
	v_readlane_b32 s41, v241, 42
	v_readlane_b32 s42, v241, 43
	v_readlane_b32 s43, v241, 44
	v_readlane_b32 s44, v241, 45
	v_readlane_b32 s45, v241, 46
	v_readlane_b32 s46, v241, 47
	v_readlane_b32 s47, v241, 48
	v_readlane_b32 s48, v241, 49
	v_readlane_b32 s49, v241, 50
	s_add_u32 s28, s68, 0x7800000
	v_lshlrev_b32_e32 v130, 1, v0
	v_mov_b32_e32 v131, v129
	v_lshlrev_b32_e32 v134, 1, v2
	v_mov_b32_e32 v135, v129
	v_and_b32_e32 v154, 15, v178
	v_xor_b32_e32 v156, 64, v155
	v_lshlrev_b32_e32 v157, 7, v180
	v_and_or_b32 v159, v178, s0, v158
	v_and_b32_e32 v160, 0xcf, v178
	v_or_b32_e32 v162, 16, v161
	v_or_b32_e32 v163, 32, v161
	v_or_b32_e32 v164, 48, v161
	s_addc_u32 s29, s69, 0
	v_lshl_add_u64 v[132:133], s[68:69], 0, v[130:131]
	v_lshl_add_u64 v[136:137], s[68:69], 0, v[134:135]
	s_mov_b64 s[2:3], 0
	v_cndmask_b32_e64 v165, 0, 1, s[12:13]
	s_mov_b64 s[38:39], 0x80
	s_mov_b64 s[40:41], 0x12000080
	s_mov_b64 s[42:43], 0x4080
	s_mov_b64 s[44:45], 0x12004080
	s_mov_b64 s[46:47], 0x8080
	s_mov_b64 s[48:49], 0x12008080
	s_mov_b64 s[50:51], 0xc080
	s_mov_b64 s[52:53], 0x1200c080
	s_movk_i32 s96, 0x2000
	s_movk_i32 s30, 0x1fff
	s_movk_i32 s31, 0x7ff
	s_movk_i32 s34, 0x3ff
	s_mov_b32 s54, 0x3e38aa3b
	s_movk_i32 s35, 0x1400
	v_lshlrev_b32_e32 v138, 1, v0
	v_lshlrev_b32_e32 v140, 1, v2
	v_mov_b32_e32 v166, 0x100
	v_mov_b32_e32 v167, 0x8f
	v_mov_b32_e32 v168, 0x78f
	v_mov_b32_e32 v169, 0x9f
	v_mov_b32_e32 v170, 0x79f
	v_mov_b32_e32 v171, 0xaf
	v_mov_b32_e32 v172, 0x7af
	v_mov_b32_e32 v173, 0xbf
	v_mov_b32_e32 v174, 0x7bf
	v_mov_b32_e32 v175, 0xcf
	v_mov_b32_e32 v176, 0x7cf
	v_mov_b32_e32 v177, 0xdf
	v_mov_b32_e32 v187, 0x7df
	v_mov_b32_e32 v188, 0xef
	v_mov_b32_e32 v189, 0x7ef
	v_mov_b32_e32 v190, 0xff
	v_mov_b32_e32 v191, 0x7ff
	v_mov_b32_e32 v192, 0x50
	v_mov_b32_e32 v193, 0x60
	v_mov_b32_e32 v194, 0x70
	v_readlane_b32 s37, v241, 38
	s_branch .LBB0_1601
.LBB0_1600:
	s_mov_b64 s[2:3], -1
	s_and_b64 vcc, exec, s[56:57]
	s_cbranch_vccnz .LBB0_2202

.LBB0_2074:
	v_readfirstlane_b32 s100, v178
	s_nop 0
	s_lshr_b32 s100, s100, 6
	s_lshr_b32 s101, s100, 2
	s_and_b32 s100, s100, 3
	s_lshl_b32 s101, s101, 7
	s_add_i32 s101, s101, s36
	s_lshl_b32 s100, s100, 6
	v_readfirstlane_b32 s4, v178
	s_nop 0
	s_lshr_b32 s4, s4, 6
	s_mul_i32 s4, s4, 4352
	s_add_i32 s4, s4, 0x10000
	v_and_b32_e32 v245, 15, v178
	v_bfe_u32 v246, v178, 4, 2
	v_mul_u32_u24_e32 v242, 272, v245
	v_mul_u32_u24_e32 v243, 272, v246
	v_lshl_add_u32 v242, v246, 3, v242
	v_lshl_add_u32 v243, v245, 4, v243
	v_add_u32_e32 v242, s4, v242
	v_add_u32_e32 v243, s4, v243
	s_sub_i32 s2, s58, 0x800
	s_add_i32 s2, s2, s100
	s_lshr_b32 s3, s2, 7
	s_and_b32 s4, s2, 0x7f
	s_cmpk_ge_u32 s36, 0x2000
	s_cbranch_scc1 .Lepiv119_smp
	s_lshr_b32 s5, s101, 8
	s_lshl_b32 s6, s5, 3
	s_add_i32 s6, s6, s3
	s_lshl_b32 s6, s6, 7
	s_add_i32 s6, s6, s4
	s_lshl_b32 s6, s6, 9
	s_and_b32 s7, s101, 0xff
	s_lshl_b32 vcc_lo, s7, 1
	s_add_u32 s6, s6, vcc_lo
	s_add_u32 s98, s26, s6
	s_addc_u32 s99, s27, 0
	s_lshl_b32 s5, s5, 1
	s_add_i32 s5, s5, 1
	s_lshl_b32 s5, s5, 8
	s_add_i32 s5, s5, s7
	s_lshl_b32 s5, s5, 12
	s_lshl_b32 s2, s2, 2
	s_add_u32 s5, s5, s2
	s_add_u32 s2, s24, s5
	s_addc_u32 s3, s25, 0
	s_movk_i32 s7, 0x800
	v_lshlrev_b32_e32 v244, 9, v246
	v_lshl_add_u32 v244, v245, 4, v244
	v_lshlrev_b32_e32 v247, 14, v246
	v_lshl_add_u32 v247, v245, 2, v247
	v_add_u32_e32 v248, 0x1000, v247
	v_add_u32_e32 v249, 0x2000, v247
	v_add_u32_e32 v250, 0x3000, v247
	global_store_dword v247, v124, s[2:3]
	global_store_dword v248, v125, s[2:3]
	global_store_dword v249, v126, s[2:3]
	global_store_dword v250, v127, s[2:3]
	s_add_u32 s2, s2, 0x10000
	s_addc_u32 s3, s3, 0
	v_cvt_pk_bf16_f32 v124, v124, v125
	v_cvt_pk_bf16_f32 v125, v126, v127
	ds_write_b64 v242, v[124:125]
	global_store_dword v247, v108, s[2:3]
	global_store_dword v248, v109, s[2:3]
	global_store_dword v249, v110, s[2:3]
	global_store_dword v250, v111, s[2:3]
	s_add_u32 s2, s2, 0x10000
	s_addc_u32 s3, s3, 0
	v_cvt_pk_bf16_f32 v108, v108, v109
	v_cvt_pk_bf16_f32 v109, v110, v111
	ds_write_b64 v242, v[108:109] offset:32
	global_store_dword v247, v92, s[2:3]
	global_store_dword v248, v93, s[2:3]
	global_store_dword v249, v94, s[2:3]
	global_store_dword v250, v95, s[2:3]
	s_add_u32 s2, s2, 0x10000
	s_addc_u32 s3, s3, 0
	v_cvt_pk_bf16_f32 v92, v92, v93
	v_cvt_pk_bf16_f32 v93, v94, v95
	ds_write_b64 v242, v[92:93] offset:64
	global_store_dword v247, v76, s[2:3]
	global_store_dword v248, v77, s[2:3]
	global_store_dword v249, v78, s[2:3]
	global_store_dword v250, v79, s[2:3]
	s_add_u32 s2, s2, 0x10000
	s_addc_u32 s3, s3, 0
	v_cvt_pk_bf16_f32 v76, v76, v77
	v_cvt_pk_bf16_f32 v77, v78, v79
	ds_write_b64 v242, v[76:77] offset:96
	global_store_dword v247, v60, s[2:3]
	global_store_dword v248, v61, s[2:3]
	global_store_dword v249, v62, s[2:3]
	global_store_dword v250, v63, s[2:3]
	s_add_u32 s2, s2, 0x10000
	s_addc_u32 s3, s3, 0
	v_cvt_pk_bf16_f32 v60, v60, v61
	v_cvt_pk_bf16_f32 v61, v62, v63
	ds_write_b64 v242, v[60:61] offset:128
	global_store_dword v247, v44, s[2:3]
	global_store_dword v248, v45, s[2:3]
	global_store_dword v249, v46, s[2:3]
	global_store_dword v250, v47, s[2:3]
	s_add_u32 s2, s2, 0x10000
	s_addc_u32 s3, s3, 0
	v_cvt_pk_bf16_f32 v44, v44, v45
	v_cvt_pk_bf16_f32 v45, v46, v47
	ds_write_b64 v242, v[44:45] offset:160
	global_store_dword v247, v28, s[2:3]
	global_store_dword v248, v29, s[2:3]
	global_store_dword v249, v30, s[2:3]
	global_store_dword v250, v31, s[2:3]
	s_add_u32 s2, s2, 0x10000
	s_addc_u32 s3, s3, 0
	v_cvt_pk_bf16_f32 v28, v28, v29
	v_cvt_pk_bf16_f32 v29, v30, v31
	ds_write_b64 v242, v[28:29] offset:192
	global_store_dword v247, v12, s[2:3]
	global_store_dword v248, v13, s[2:3]
	global_store_dword v249, v14, s[2:3]
	global_store_dword v250, v15, s[2:3]
	s_sub_u32 s2, s2, 0x70000
	s_subb_u32 s3, s3, 0
	v_cvt_pk_bf16_f32 v12, v12, v13
	v_cvt_pk_bf16_f32 v13, v14, v15
	ds_write_b64 v242, v[12:13] offset:224
	s_waitcnt lgkmcnt(0)
	ds_read_b128 v[124:127], v243
	ds_read_b128 v[108:111], v243 offset:1088
	ds_read_b128 v[92:95], v243 offset:2176
	ds_read_b128 v[76:79], v243 offset:3264
	s_waitcnt lgkmcnt(3)
	global_store_dwordx4 v244, v[124:127], s[98:99]
	s_add_u32 s98, s98, s7
	s_addc_u32 s99, s99, 0
	s_waitcnt lgkmcnt(2)
	global_store_dwordx4 v244, v[108:111], s[98:99]
	s_add_u32 s98, s98, s7
	s_addc_u32 s99, s99, 0
	s_waitcnt lgkmcnt(1)
	global_store_dwordx4 v244, v[92:95], s[98:99]
	s_add_u32 s98, s98, s7
	s_addc_u32 s99, s99, 0
	s_waitcnt lgkmcnt(0)
	global_store_dwordx4 v244, v[76:79], s[98:99]
	s_add_u32 s98, s98, s7
	s_addc_u32 s99, s99, 0
	global_store_dword v247, v120, s[2:3] offset:64
	global_store_dword v248, v121, s[2:3] offset:64
	global_store_dword v249, v122, s[2:3] offset:64
	global_store_dword v250, v123, s[2:3] offset:64
	s_add_u32 s2, s2, 0x10000
	s_addc_u32 s3, s3, 0
	v_cvt_pk_bf16_f32 v120, v120, v121
	v_cvt_pk_bf16_f32 v121, v122, v123
	ds_write_b64 v242, v[120:121]
	global_store_dword v247, v104, s[2:3] offset:64
	global_store_dword v248, v105, s[2:3] offset:64
	global_store_dword v249, v106, s[2:3] offset:64
	global_store_dword v250, v107, s[2:3] offset:64
	s_add_u32 s2, s2, 0x10000
	s_addc_u32 s3, s3, 0
	v_cvt_pk_bf16_f32 v104, v104, v105
	v_cvt_pk_bf16_f32 v105, v106, v107
	ds_write_b64 v242, v[104:105] offset:32
	global_store_dword v247, v88, s[2:3] offset:64
	global_store_dword v248, v89, s[2:3] offset:64
	global_store_dword v249, v90, s[2:3] offset:64
	global_store_dword v250, v91, s[2:3] offset:64
	s_add_u32 s2, s2, 0x10000
	s_addc_u32 s3, s3, 0
	v_cvt_pk_bf16_f32 v88, v88, v89
	v_cvt_pk_bf16_f32 v89, v90, v91
	ds_write_b64 v242, v[88:89] offset:64
	global_store_dword v247, v72, s[2:3] offset:64
	global_store_dword v248, v73, s[2:3] offset:64
	global_store_dword v249, v74, s[2:3] offset:64
	global_store_dword v250, v75, s[2:3] offset:64
	s_add_u32 s2, s2, 0x10000
	s_addc_u32 s3, s3, 0
	v_cvt_pk_bf16_f32 v72, v72, v73
	v_cvt_pk_bf16_f32 v73, v74, v75
	ds_write_b64 v242, v[72:73] offset:96
	global_store_dword v247, v56, s[2:3] offset:64
	global_store_dword v248, v57, s[2:3] offset:64
	global_store_dword v249, v58, s[2:3] offset:64
	global_store_dword v250, v59, s[2:3] offset:64
	s_add_u32 s2, s2, 0x10000
	s_addc_u32 s3, s3, 0
	v_cvt_pk_bf16_f32 v56, v56, v57
	v_cvt_pk_bf16_f32 v57, v58, v59
	ds_write_b64 v242, v[56:57] offset:128
	global_store_dword v247, v40, s[2:3] offset:64
	global_store_dword v248, v41, s[2:3] offset:64
	global_store_dword v249, v42, s[2:3] offset:64
	global_store_dword v250, v43, s[2:3] offset:64
	s_add_u32 s2, s2, 0x10000
	s_addc_u32 s3, s3, 0
	v_cvt_pk_bf16_f32 v40, v40, v41
	v_cvt_pk_bf16_f32 v41, v42, v43
	ds_write_b64 v242, v[40:41] offset:160
	global_store_dword v247, v24, s[2:3] offset:64
	global_store_dword v248, v25, s[2:3] offset:64
	global_store_dword v249, v26, s[2:3] offset:64
	global_store_dword v250, v27, s[2:3] offset:64
	s_add_u32 s2, s2, 0x10000
	s_addc_u32 s3, s3, 0
	v_cvt_pk_bf16_f32 v24, v24, v25
	v_cvt_pk_bf16_f32 v25, v26, v27
	ds_write_b64 v242, v[24:25] offset:192
	global_store_dword v247, v8, s[2:3] offset:64
	global_store_dword v248, v9, s[2:3] offset:64
	global_store_dword v249, v10, s[2:3] offset:64
	global_store_dword v250, v11, s[2:3] offset:64
	s_sub_u32 s2, s2, 0x70000
	s_subb_u32 s3, s3, 0
	v_cvt_pk_bf16_f32 v8, v8, v9
	v_cvt_pk_bf16_f32 v9, v10, v11
	ds_write_b64 v242, v[8:9] offset:224
	s_waitcnt lgkmcnt(0)
	ds_read_b128 v[120:123], v243
	ds_read_b128 v[104:107], v243 offset:1088
	ds_read_b128 v[88:91], v243 offset:2176
	ds_read_b128 v[72:75], v243 offset:3264
	s_waitcnt lgkmcnt(3)
	global_store_dwordx4 v244, v[120:123], s[98:99]
	s_add_u32 s98, s98, s7
	s_addc_u32 s99, s99, 0
	s_waitcnt lgkmcnt(2)
	global_store_dwordx4 v244, v[104:107], s[98:99]
	s_add_u32 s98, s98, s7
	s_addc_u32 s99, s99, 0
	s_waitcnt lgkmcnt(1)
	global_store_dwordx4 v244, v[88:91], s[98:99]
	s_add_u32 s98, s98, s7
	s_addc_u32 s99, s99, 0
	s_waitcnt lgkmcnt(0)
	global_store_dwordx4 v244, v[72:75], s[98:99]
	s_add_u32 s98, s98, s7
	s_addc_u32 s99, s99, 0
	global_store_dword v247, v116, s[2:3] offset:128
	global_store_dword v248, v117, s[2:3] offset:128
	global_store_dword v249, v118, s[2:3] offset:128
	global_store_dword v250, v119, s[2:3] offset:128
	s_add_u32 s2, s2, 0x10000
	s_addc_u32 s3, s3, 0
	v_cvt_pk_bf16_f32 v116, v116, v117
	v_cvt_pk_bf16_f32 v117, v118, v119
	ds_write_b64 v242, v[116:117]
	global_store_dword v247, v100, s[2:3] offset:128
	global_store_dword v248, v101, s[2:3] offset:128
	global_store_dword v249, v102, s[2:3] offset:128
	global_store_dword v250, v103, s[2:3] offset:128
	s_add_u32 s2, s2, 0x10000
	s_addc_u32 s3, s3, 0
	v_cvt_pk_bf16_f32 v100, v100, v101
	v_cvt_pk_bf16_f32 v101, v102, v103
	ds_write_b64 v242, v[100:101] offset:32
	global_store_dword v247, v84, s[2:3] offset:128
	global_store_dword v248, v85, s[2:3] offset:128
	global_store_dword v249, v86, s[2:3] offset:128
	global_store_dword v250, v87, s[2:3] offset:128
	s_add_u32 s2, s2, 0x10000
	s_addc_u32 s3, s3, 0
	v_cvt_pk_bf16_f32 v84, v84, v85
	v_cvt_pk_bf16_f32 v85, v86, v87
	ds_write_b64 v242, v[84:85] offset:64
	global_store_dword v247, v68, s[2:3] offset:128
	global_store_dword v248, v69, s[2:3] offset:128
	global_store_dword v249, v70, s[2:3] offset:128
	global_store_dword v250, v71, s[2:3] offset:128
	s_add_u32 s2, s2, 0x10000
	s_addc_u32 s3, s3, 0
	v_cvt_pk_bf16_f32 v68, v68, v69
	v_cvt_pk_bf16_f32 v69, v70, v71
	ds_write_b64 v242, v[68:69] offset:96
	global_store_dword v247, v52, s[2:3] offset:128
	global_store_dword v248, v53, s[2:3] offset:128
	global_store_dword v249, v54, s[2:3] offset:128
	global_store_dword v250, v55, s[2:3] offset:128
	s_add_u32 s2, s2, 0x10000
	s_addc_u32 s3, s3, 0
	v_cvt_pk_bf16_f32 v52, v52, v53
	v_cvt_pk_bf16_f32 v53, v54, v55
	ds_write_b64 v242, v[52:53] offset:128
	global_store_dword v247, v36, s[2:3] offset:128
	global_store_dword v248, v37, s[2:3] offset:128
	global_store_dword v249, v38, s[2:3] offset:128
	global_store_dword v250, v39, s[2:3] offset:128
	s_add_u32 s2, s2, 0x10000
	s_addc_u32 s3, s3, 0
	v_cvt_pk_bf16_f32 v36, v36, v37
	v_cvt_pk_bf16_f32 v37, v38, v39
	ds_write_b64 v242, v[36:37] offset:160
	global_store_dword v247, v20, s[2:3] offset:128
	global_store_dword v248, v21, s[2:3] offset:128
	global_store_dword v249, v22, s[2:3] offset:128
	global_store_dword v250, v23, s[2:3] offset:128
	s_add_u32 s2, s2, 0x10000
	s_addc_u32 s3, s3, 0
	v_cvt_pk_bf16_f32 v20, v20, v21
	v_cvt_pk_bf16_f32 v21, v22, v23
	ds_write_b64 v242, v[20:21] offset:192
	global_store_dword v247, v4, s[2:3] offset:128
	global_store_dword v248, v5, s[2:3] offset:128
	global_store_dword v249, v6, s[2:3] offset:128
	global_store_dword v250, v7, s[2:3] offset:128
	s_sub_u32 s2, s2, 0x70000
	s_subb_u32 s3, s3, 0
	v_cvt_pk_bf16_f32 v4, v4, v5
	v_cvt_pk_bf16_f32 v5, v6, v7
	ds_write_b64 v242, v[4:5] offset:224
	s_waitcnt lgkmcnt(0)
	ds_read_b128 v[116:119], v243
	ds_read_b128 v[100:103], v243 offset:1088
	ds_read_b128 v[84:87], v243 offset:2176
	ds_read_b128 v[68:71], v243 offset:3264
	s_waitcnt lgkmcnt(3)
	global_store_dwordx4 v244, v[116:119], s[98:99]
	s_add_u32 s98, s98, s7
	s_addc_u32 s99, s99, 0
	s_waitcnt lgkmcnt(2)
	global_store_dwordx4 v244, v[100:103], s[98:99]
	s_add_u32 s98, s98, s7
	s_addc_u32 s99, s99, 0
	s_waitcnt lgkmcnt(1)
	global_store_dwordx4 v244, v[84:87], s[98:99]
	s_add_u32 s98, s98, s7
	s_addc_u32 s99, s99, 0
	s_waitcnt lgkmcnt(0)
	global_store_dwordx4 v244, v[68:71], s[98:99]
	s_add_u32 s98, s98, s7
	s_addc_u32 s99, s99, 0
	global_store_dword v247, v112, s[2:3] offset:192
	global_store_dword v248, v113, s[2:3] offset:192
	global_store_dword v249, v114, s[2:3] offset:192
	global_store_dword v250, v115, s[2:3] offset:192
	s_add_u32 s2, s2, 0x10000
	s_addc_u32 s3, s3, 0
	v_cvt_pk_bf16_f32 v112, v112, v113
	v_cvt_pk_bf16_f32 v113, v114, v115
	ds_write_b64 v242, v[112:113]
	global_store_dword v247, v96, s[2:3] offset:192
	global_store_dword v248, v97, s[2:3] offset:192
	global_store_dword v249, v98, s[2:3] offset:192
	global_store_dword v250, v99, s[2:3] offset:192
	s_add_u32 s2, s2, 0x10000
	s_addc_u32 s3, s3, 0
	v_cvt_pk_bf16_f32 v96, v96, v97
	v_cvt_pk_bf16_f32 v97, v98, v99
	ds_write_b64 v242, v[96:97] offset:32
	global_store_dword v247, v80, s[2:3] offset:192
	global_store_dword v248, v81, s[2:3] offset:192
	global_store_dword v249, v82, s[2:3] offset:192
	global_store_dword v250, v83, s[2:3] offset:192
	s_add_u32 s2, s2, 0x10000
	s_addc_u32 s3, s3, 0
	v_cvt_pk_bf16_f32 v80, v80, v81
	v_cvt_pk_bf16_f32 v81, v82, v83
	ds_write_b64 v242, v[80:81] offset:64
	global_store_dword v247, v64, s[2:3] offset:192
	global_store_dword v248, v65, s[2:3] offset:192
	global_store_dword v249, v66, s[2:3] offset:192
	global_store_dword v250, v67, s[2:3] offset:192
	s_add_u32 s2, s2, 0x10000
	s_addc_u32 s3, s3, 0
	v_cvt_pk_bf16_f32 v64, v64, v65
	v_cvt_pk_bf16_f32 v65, v66, v67
	ds_write_b64 v242, v[64:65] offset:96
	global_store_dword v247, v48, s[2:3] offset:192
	global_store_dword v248, v49, s[2:3] offset:192
	global_store_dword v249, v50, s[2:3] offset:192
	global_store_dword v250, v51, s[2:3] offset:192
	s_add_u32 s2, s2, 0x10000
	s_addc_u32 s3, s3, 0
	v_cvt_pk_bf16_f32 v48, v48, v49
	v_cvt_pk_bf16_f32 v49, v50, v51
	ds_write_b64 v242, v[48:49] offset:128
	global_store_dword v247, v32, s[2:3] offset:192
	global_store_dword v248, v33, s[2:3] offset:192
	global_store_dword v249, v34, s[2:3] offset:192
	global_store_dword v250, v35, s[2:3] offset:192
	s_add_u32 s2, s2, 0x10000
	s_addc_u32 s3, s3, 0
	v_cvt_pk_bf16_f32 v32, v32, v33
	v_cvt_pk_bf16_f32 v33, v34, v35
	ds_write_b64 v242, v[32:33] offset:160
	global_store_dword v247, v16, s[2:3] offset:192
	global_store_dword v248, v17, s[2:3] offset:192
	global_store_dword v249, v18, s[2:3] offset:192
	global_store_dword v250, v19, s[2:3] offset:192
	s_add_u32 s2, s2, 0x10000
	s_addc_u32 s3, s3, 0
	v_cvt_pk_bf16_f32 v16, v16, v17
	v_cvt_pk_bf16_f32 v17, v18, v19
	ds_write_b64 v242, v[16:17] offset:192
	global_store_dword v247, v0, s[2:3] offset:192
	global_store_dword v248, v1, s[2:3] offset:192
	global_store_dword v249, v2, s[2:3] offset:192
	global_store_dword v250, v3, s[2:3] offset:192
	s_sub_u32 s2, s2, 0x70000
	s_subb_u32 s3, s3, 0
	v_cvt_pk_bf16_f32 v0, v0, v1
	v_cvt_pk_bf16_f32 v1, v2, v3
	ds_write_b64 v242, v[0:1] offset:224
	s_waitcnt lgkmcnt(0)
	ds_read_b128 v[112:115], v243
	ds_read_b128 v[96:99], v243 offset:1088
	ds_read_b128 v[80:83], v243 offset:2176
	ds_read_b128 v[64:67], v243 offset:3264
	s_waitcnt lgkmcnt(3)
	global_store_dwordx4 v244, v[112:115], s[98:99]
	s_add_u32 s98, s98, s7
	s_addc_u32 s99, s99, 0
	s_waitcnt lgkmcnt(2)
	global_store_dwordx4 v244, v[96:99], s[98:99]
	s_add_u32 s98, s98, s7
	s_addc_u32 s99, s99, 0
	s_waitcnt lgkmcnt(1)
	global_store_dwordx4 v244, v[80:83], s[98:99]
	s_add_u32 s98, s98, s7
	s_addc_u32 s99, s99, 0
	s_waitcnt lgkmcnt(0)
	global_store_dwordx4 v244, v[64:67], s[98:99]
	s_branch .LBB0_1600
